# GEMM tile order: 6 row tiles per column-major group instead of 8 (multiplies instead of shifts)
# speedup vs baseline: 1.0166x; 1.0166x over previous
;     __device__ bool next(int i, Unit& u) const {
;         const long L = (long)i * G + c; if (L >= nwg) return false;
;         int wgid = (int)L; { const int q = nwg / NXCD, r = nwg % NXCD, xcd = wgid % NXCD, off = wgid / NXCD; wgid = (xcd < r ? xcd * (q + 1) : r * (q + 1) + (xcd - r) * q) + off; }
;         const int nig = WGM * nN, gid = wgid / nig, fm = gid * WGM, gsz = (nM - fm) < WGM ? (nM - fm) : WGM;
;         u.pm = fm + ((wgid % nig) % gsz); u.pn = (wgid % nig) / gsz; return true;
;     }
.LBB0_254:
	s_mul_i32 s4, s18, 6
	v_cvt_f32_u32_e32 v0, s4
	s_ashr_i32 s5, s8, 3
	s_sub_i32 s8, 0, s4
	s_add_i32 s5, s13, s5
	v_rcp_iflag_f32_e32 v0, v0
	s_abs_i32 s14, s5
	s_ashr_i32 s13, s5, 31
	v_mul_f32_e32 v0, 0x4f7ffffe, v0
	v_cvt_u32_f32_e32 v0, v0
	s_nop 0
	v_readfirstlane_b32 s15, v0
	s_mul_i32 s8, s8, s15
	s_mul_hi_u32 s8, s15, s8
	s_add_i32 s15, s15, s8
	s_mul_hi_u32 s8, s14, s15
	s_mul_i32 s15, s8, s4
	s_sub_i32 s14, s14, s15
	s_add_i32 s19, s8, 1
	s_sub_i32 s15, s14, s4
	s_cmp_ge_u32 s14, s4
	s_cselect_b32 s8, s19, s8
	s_cselect_b32 s14, s15, s14
	s_add_i32 s15, s8, 1
	s_cmp_ge_u32 s14, s4
	s_cselect_b32 s8, s15, s8
	s_xor_b32 s8, s8, s13
	s_sub_i32 s8, s8, s13
	s_mul_i32 s13, s8, 6
	s_mul_i32 s8, s8, s4
	s_sub_i32 s4, s96, s13
	s_min_i32 s14, s4, 6
	s_sext_i32_i16 s4, s14
	v_cvt_f32_i32_e32 v0, s4
	s_sub_i32 s8, s5, s8
	s_sext_i32_i16 s5, s8
	v_cvt_f32_i32_e32 v2, s5
	v_rcp_iflag_f32_e32 v3, v0
	s_xor_b32 s4, s5, s4
	s_ashr_i32 s4, s4, 30
	s_or_b32 s15, s4, 1
	v_mul_f32_e32 v3, v2, v3
	v_trunc_f32_e32 v3, v3
	v_fma_f32 v2, -v3, v0, v2
	v_cvt_i32_f32_e32 v3, v3
	v_cmp_ge_f32_e64 s[4:5], |v2|, |v0|
	s_and_b64 s[4:5], s[4:5], exec
	s_cselect_b32 s4, s15, 0
	v_readfirstlane_b32 s5, v3
	s_add_i32 s4, s5, s4
	s_sext_i32_i16 s71, s4
	s_mul_i32 s4, s4, s14
	s_sub_i32 s4, s8, s4
	s_sext_i32_i16 s4, s4
	s_add_i32 s63, s13, s4

; __device__ __forceinline__ int opaque_tid(int wv) { int t = wv * 64 + (int)__builtin_amdgcn_mbcnt_hi(~0u, __builtin_amdgcn_mbcnt_lo(~0u, 0u)); asm volatile("" : "+v"(t)); return t; }
; #define PG8_STAGE(bufoff, gbase, voff) do { _Pragma("unroll") for (int _i = 0; _i < 2; ++_i) \
;         __builtin_amdgcn_global_load_lds((const unsigned*)((const char*)(gbase) + (voff)[_i]), (LAS unsigned*)(lds + (bufoff) + ldsw + _i * 8192), 16, 0, 0); } while (0)
; #define PG8_WAIT_V(n) asm volatile("s_waitcnt vmcnt(" #n ")" ::: "memory")
; #define PG8_BAR __builtin_amdgcn_s_barrier()
; template <class EpiT>
; __device__ __forceinline__ void gemm_phase(LAS unsigned char* lds, const Gemm g, const StaticOrder& S, const EpiT& E, int wv) {
;     const int tid = opaque_tid(wv), wid = __builtin_amdgcn_readfirstlane(tid >> 6), lane = tid & 63, wr = wid >> 2, wc = wid & 3, fr = lane & 15, fq = lane >> 4;
;     int K = g.K; asm volatile("" : "+s"(K)); const int nt = K / BK;
;     unsigned voffA[2], voffB[2];
; #pragma unroll
;     for (int i = 0; i < 2; ++i) { int R, C; stage_rc(tid * 16 + i * 8192, R, C); const int Rb = (R & ~31) + perm32(R & 31);
;         voffA[i] = (unsigned)(R * g.lda + C) * 2u; voffB[i] = (unsigned)(Rb * g.ldb + C) * 2u; }
;     const size_t kstep = (size_t)(BK * 2);
;     const size_t hA = (size_t)HALF * g.lda * 2, hB = (size_t)HALF * g.ldb * 2;
;     const size_t tA = 2 * hA, tB = 2 * hB;
;     const unsigned ldsw = (unsigned)wid * 1024u;
;     const int aoff = lds_byte(wr * 64 + fr, fq * 8), boff = lds_byte(wc * 32 + fr, fq * 8);
;     ...
;     const char* cA = (const char*)g.A + (size_t)cur.pm * tA + (size_t)cur.pn * g.apn * 2; const char* cB = (const char*)g.Bt + (size_t)cur.pn * tB;
;     PG8_STAGE(PG8_SB(0, 0), cB, voffB); PG8_STAGE(PG8_SB(0, 1), cB + hB, voffB); PG8_STAGE(PG8_SA(0, 0), cA, voffA); PG8_STAGE(PG8_SA(0, 1), cA + hA, voffA);
;     if (wr == 1) PG8_BAR;
;     PG8_WAIT_V(2); PG8_BAR;
;     PG8_STAGE(PG8_SB(1, 0), cB + kstep, voffB); PG8_STAGE(PG8_SA(1, 0), cA + kstep, voffA); PG8_STAGE(PG8_SB(1, 1), cB + hB + kstep, voffB);
;     PG8_WAIT_V(6); PG8_BAR;
.LBB0_258:
	s_add_i32 m0, s14, 0x18000
	v_lshl_add_u64 v[4:5], v[4:5], 0, s[10:11]
	s_waitcnt vmcnt(2)
	s_barrier
	global_load_lds_dwordx4 v[4:5], off
	v_lshl_add_u64 v[4:5], v[6:7], 0, s[10:11]
	s_add_i32 m0, s14, 0x1a000
	s_add_i32 s72, s14, 0x8000
	global_load_lds_dwordx4 v[4:5], off
	v_lshl_add_u64 v[4:5], v[12:13], 0, s[10:11]
	s_mov_b32 m0, s72
	s_add_i32 s73, s14, 0xa000
	global_load_lds_dwordx4 v[4:5], off
	v_lshl_add_u64 v[4:5], v[18:19], 0, s[10:11]
	s_mov_b32 m0, s73
	s_and_b32 s80, s0, 3
	global_load_lds_dwordx4 v[4:5], off
	s_add_i32 m0, s14, 0x1c000
	v_lshl_add_u64 v[4:5], v[8:9], 0, s[10:11]
	global_load_lds_dwordx4 v[4:5], off
	v_lshl_add_u64 v[4:5], v[10:11], 0, s[10:11]
	s_add_i32 m0, s14, 0x1e000
	s_ashr_i32 s0, s16, 31
	global_load_lds_dwordx4 v[4:5], off
	v_bfe_u32 v9, v20, 4, 2
	s_lshr_b32 s0, s0, 26
	v_and_b32_e32 v7, 15, v20
	s_add_i32 s0, s16, s0
	v_lshlrev_b32_e32 v6, 4, v9
	v_lshlrev_b32_e32 v8, 2, v20
	s_ashr_i32 s81, s0, 6
	v_lshl_or_b32 v17, s1, 6, v7
	v_lshl_or_b32 v7, v7, 6, v6
	s_lshl_b32 s0, s1, 13
	v_and_b32_e32 v8, 32, v8
	v_bitop3_b32 v12, v7, s0, v8 bitop3:0xde
	s_lshl_b32 s0, s80, 12
	s_cmp_gt_i32 s16, 63
	s_cselect_b64 s[68:69], -1, 0
	s_add_i32 s52, s81, -2
	s_cmpk_lt_u32 s17, 0x100
	s_cselect_b64 s[16:17], -1, 0
	s_mul_i32 s57, s18, 6
	v_bitop3_b32 v234, v7, s0, v8 bitop3:0xde
	v_cvt_f32_u32_e32 v7, s57
	v_lshlrev_b32_e32 v0, 3, v9
	v_lshlrev_b32_e32 v8, 2, v9
	v_cmp_eq_u32_e64 s[82:83], 0, v9
	v_lshlrev_b32_e32 v10, 5, v9
	v_rcp_iflag_f32_e32 v9, v7
	s_lshr_b32 s0, s84, 3
	v_writelane_b32 v255, s0, 36
	s_add_i32 s99, s0, 1
	v_mul_f32_e32 v9, 0x4f7ffffe, v9
	v_cvt_u32_f32_e32 v9, v9
	v_readlane_b32 s0, v254, 50
	v_mov_b32_e32 v11, v1
	v_readlane_b32 s1, v254, 51
	v_mov_b32_e32 v7, v1
	s_waitcnt vmcnt(6)
	v_mov_b32_e32 v3, v2
	v_lshl_add_u64 v[188:189], s[0:1], 0, v[10:11]
	v_lshl_add_u64 v[190:191], s[0:1], 0, v[6:7]
	s_sub_i32 s0, 0, s57
	v_readfirstlane_b32 s1, v9
	s_mul_i32 s0, s0, s1
	s_mul_hi_u32 s0, s1, s0
	s_add_i32 s55, s1, s0
	v_readlane_b32 s0, v255, 22
	v_readlane_b32 s1, v255, 23
	v_mov_b32_e32 v4, v2
	v_mov_b32_e32 v5, v2
	v_lshl_add_u64 v[192:193], s[0:1], 0, v[0:1]
	v_readlane_b32 s0, v255, 24
	v_readlane_b32 s1, v255, 25
	v_or_b32_e32 v235, 16, v17
	v_or_b32_e32 v236, 32, v17
	v_lshl_add_u64 v[194:195], s[0:1], 0, v[6:7]
	v_add_u32_e32 v6, v23, v21
	v_add_lshl_u32 v6, v6, v22, 1
	v_lshl_add_u64 v[196:197], s[4:5], 0, v[6:7]
	v_add_u32_e32 v6, v26, v24
	v_add_lshl_u32 v6, v6, v25, 1
	v_or_b32_e32 v237, 48, v17
	v_add_u32_e32 v238, 0x90, v17
	v_add_u32_e32 v239, 0xa0, v17
	v_add_u32_e32 v240, 0xb0, v17
	s_mov_b32 s53, 0
	s_ashr_i32 s54, s70, 31
	s_mov_b32 s85, s91
	s_and_b32 s56, s84, 6
	v_lshl_or_b32 v241, s80, 5, v0
	v_lshl_add_u64 v[198:199], s[4:5], 0, v[6:7]
	v_add_u32_e32 v242, 0, v12
	v_lshlrev_b32_e32 v200, 1, v0
	v_lshlrev_b32_e32 v202, 1, v8
	s_barrier
	s_branch .LBB0_261

;     __device__ bool next(int i, Unit& u) const {
;         const long L = (long)i * G + c; if (L >= nwg) return false;
;         int wgid = (int)L; { const int q = nwg / NXCD, r = nwg % NXCD, xcd = wgid % NXCD, off = wgid / NXCD; wgid = (xcd < r ? xcd * (q + 1) : r * (q + 1) + (xcd - r) * q) + off; }
;         const int nig = WGM * nN, gid = wgid / nig, fm = gid * WGM, gsz = (nM - fm) < WGM ? (nM - fm) : WGM;
;         u.pm = fm + ((wgid % nig) % gsz); u.pn = (wgid % nig) / gsz; return true;
;     }
.LBB0_266:
	s_ashr_i32 s5, s5, 3
	s_add_i32 s5, s21, s5
	s_abs_i32 s19, s5
	s_mul_hi_u32 s20, s19, s55
	s_mul_i32 s21, s20, s57
	s_sub_i32 s19, s19, s21
	s_ashr_i32 s18, s5, 31
	s_add_i32 s21, s20, 1
	s_sub_i32 s22, s19, s57
	s_cmp_ge_u32 s19, s57
	s_cselect_b32 s20, s21, s20
	s_cselect_b32 s19, s22, s19
	s_add_i32 s21, s20, 1
	s_cmp_ge_u32 s19, s57
	s_cselect_b32 s19, s21, s20
	s_xor_b32 s19, s19, s18
	s_sub_i32 s18, s19, s18
	s_mul_i32 s19, s18, 6
	s_sub_i32 s20, s96, s19
	s_min_i32 s20, s20, 6
	s_abs_i32 s21, s20
	v_cvt_f32_u32_e32 v0, s21
	s_sub_i32 s23, 0, s21
	s_mul_i32 s18, s18, s57
	s_sub_i32 s18, s5, s18
	v_rcp_iflag_f32_e32 v0, v0
	s_abs_i32 s5, s18
	s_xor_b32 s22, s18, s20
	s_ashr_i32 s22, s22, 31
	v_mul_f32_e32 v0, 0x4f7ffffe, v0
	v_cvt_u32_f32_e32 v0, v0
	s_nop 0
	v_readfirstlane_b32 s38, v0
	s_mul_i32 s23, s23, s38
	s_mul_hi_u32 s23, s38, s23
	s_add_i32 s38, s38, s23
	s_mul_hi_u32 s23, s5, s38
	s_mul_i32 s38, s23, s21
	s_sub_i32 s5, s5, s38
	s_add_i32 s38, s23, 1
	s_sub_i32 s39, s5, s21
	s_cmp_ge_u32 s5, s21
	s_cselect_b32 s23, s38, s23
	s_cselect_b32 s5, s39, s5
	s_add_i32 s38, s23, 1
	s_cmp_ge_u32 s5, s21
	s_cselect_b32 s5, s38, s23
	s_xor_b32 s5, s5, s22
	s_sub_i32 s5, s5, s22
	s_mul_i32 s20, s5, s20
	s_sub_i32 s18, s18, s20
	s_add_i32 s62, s18, s19
